# v41 plus top-k: 30 single-use copy+canonicalise v_max moves folded into their consumers
# speedup vs baseline: 1.0009x; 1.0009x over previous
; #define LAS __attribute__((address_space(3)))
; DI void ce_desc(float& hi, float& lo) { const float a = hi, b = lo; hi = fmaxf(a, b); lo = fminf(a, b); }
; DI void bitonic_merge16(float (&v)[16]) {
; #pragma unroll
;   for (int j = 8; j > 0; j >>= 1)
; #pragma unroll
;     for (int i = 0; i < 16; ++i) if ((i & j) == 0) ce_desc(v[i], v[i | j]);
; }
; DI void bitonic_sort16(float (&v)[16]) {
; #pragma unroll
;   for (int k = 2; k <= 16; k <<= 1)
; #pragma unroll
;     for (int j = k >> 1; j > 0; j >>= 1)
; #pragma unroll
;       for (int i = 0; i < 16; ++i) {
;         const int l = i ^ j;
;         if (l > i) { if ((i & k) == 0 || k == 16) ce_desc(v[i], v[l]); else ce_desc(v[l], v[i]); }
;       }
; }
; DI void merge_top16(float (&v)[16], const float (&w)[16]) {
; #pragma unroll
;   for (int i = 0; i < 16; ++i) v[i] = fmaxf(v[i], w[15 - i]);
;   bitonic_merge16(v);
; DI void gemm256_tile(const Params& p, int mode, int layer, const u16* R, const u16* Cc, int brow, int bcol, lchar* shm, int tid_in, int wid) {
;     ...
;       if (kh == 0) {
;         float wk[16];
; #pragma unroll
;         for (int q = 0; q < 4; ++q) {
;           const f32x4 xv = *(const LAS f32x4*)((lchar*)S + tok * 80 + 16 * q);
;           wk[4 * q] = xv[0]; wk[4 * q + 1] = xv[1]; wk[4 * q + 2] = xv[2]; wk[4 * q + 3] = xv[3];
;         }
;         merge_top16(v, wk);
.LBB0_225:
	s_and_b64 vcc, exec, s[4:5]
	s_waitcnt lgkmcnt(0)
	s_barrier
	s_cbranch_vccnz .LBB0_227
	ds_read_b128 v[148:151], v166 offset:48
	ds_read_b128 v[152:155], v166 offset:32
	ds_read_b128 v[156:159], v166
	ds_read_b128 v[168:171], v166 offset:16
	s_waitcnt lgkmcnt(3)
	v_max_f32_e32 v143, v143, v148
	s_waitcnt lgkmcnt(2)
	v_max_f32_e32 v136, v136, v155
	v_max_f32_e32 v137, v137, v154
	v_max_f32_e32 v138, v138, v153
	v_max_f32_e32 v139, v139, v152
	s_waitcnt lgkmcnt(0)
	v_max_f32_e32 v132, v132, v171
	v_max_f32_e32 v133, v133, v170
	v_max_f32_e32 v134, v134, v169
	v_max_f32_e32 v135, v135, v168
	v_max_f32_e32 v128, v128, v159
	v_max_f32_e32 v129, v129, v158
	v_max_f32_e32 v130, v130, v157
	v_max_f32_e32 v140, v140, v151
	v_max_f32_e32 v141, v141, v150
	v_max_f32_e32 v142, v142, v149
	v_max_f32_e32 v131, v131, v156
	v_max_f32_e32 v148, v140, v132
	v_min_f32_e32 v132, v140, v132
	v_max_f32_e32 v140, v141, v133
	v_min_f32_e32 v133, v141, v133
	v_max_f32_e32 v141, v142, v134
	v_min_f32_e32 v134, v142, v134
	v_max_f32_e32 v142, v143, v135
	v_min_f32_e32 v135, v143, v135
	v_max_f32_e32 v143, v136, v128
	v_min_f32_e32 v128, v136, v128
	v_max_f32_e32 v136, v137, v129
	v_min_f32_e32 v129, v137, v129
	v_max_f32_e32 v137, v138, v130
	v_min_f32_e32 v130, v138, v130
	v_max_f32_e32 v138, v139, v131
	v_min_f32_e32 v131, v139, v131
	v_max_f32_e32 v139, v148, v143
	v_min_f32_e32 v143, v148, v143
	v_max_f32_e32 v148, v140, v136
	v_min_f32_e32 v136, v140, v136
	v_max_f32_e32 v140, v141, v137
	v_min_f32_e32 v137, v141, v137
	v_max_f32_e32 v141, v142, v138
	v_min_f32_e32 v138, v142, v138
	v_max_f32_e32 v142, v132, v128
	v_min_f32_e32 v128, v132, v128
	v_max_f32_e32 v132, v133, v129
	v_min_f32_e32 v129, v133, v129
	v_max_f32_e32 v133, v134, v130
	v_min_f32_e32 v130, v134, v130
	v_max_f32_e32 v134, v135, v131
	v_min_f32_e32 v131, v135, v131
	v_max_f32_e32 v135, v139, v140
	v_min_f32_e32 v139, v139, v140
	v_max_f32_e32 v149, v148, v141
	v_min_f32_e32 v148, v148, v141
	v_max_f32_e32 v150, v143, v137
	v_min_f32_e32 v151, v143, v137
	v_max_f32_e32 v137, v136, v138
	v_min_f32_e32 v152, v136, v138
	v_max_f32_e32 v153, v142, v133
	v_min_f32_e32 v154, v142, v133
	v_max_f32_e32 v133, v132, v134
	v_min_f32_e32 v155, v132, v134
	v_max_f32_e32 v156, v128, v130
	v_min_f32_e32 v157, v128, v130
	v_max_f32_e32 v130, v129, v131
	v_min_f32_e32 v131, v129, v131
	v_max_f32_e32 v140, v135, v149
	v_min_f32_e32 v141, v135, v149
	v_max_f32_e32 v142, v139, v148
	v_min_f32_e32 v143, v139, v148
	v_max_f32_e32 v136, v150, v137
	v_min_f32_e32 v137, v150, v137
	v_max_f32_e32 v138, v151, v152
	v_min_f32_e32 v139, v151, v152
	v_max_f32_e32 v132, v153, v133
	v_min_f32_e32 v133, v153, v133
	v_max_f32_e32 v134, v154, v155
	v_min_f32_e32 v135, v154, v155
	v_max_f32_e32 v128, v156, v130
	v_min_f32_e32 v129, v156, v130
	v_max_f32_e32 v130, v157, v131
	v_min_f32_e32 v131, v157, v131

; #define LAS __attribute__((address_space(3)))
; DI void ce_desc(float& hi, float& lo) { const float a = hi, b = lo; hi = fmaxf(a, b); lo = fminf(a, b); }
; DI void bitonic_merge16(float (&v)[16]) {
; #pragma unroll
;   for (int j = 8; j > 0; j >>= 1)
; #pragma unroll
;     for (int i = 0; i < 16; ++i) if ((i & j) == 0) ce_desc(v[i], v[i | j]);
; }
; DI void bitonic_sort16(float (&v)[16]) {
; #pragma unroll
;   for (int k = 2; k <= 16; k <<= 1)
; #pragma unroll
;     for (int j = k >> 1; j > 0; j >>= 1)
; #pragma unroll
;       for (int i = 0; i < 16; ++i) {
;         const int l = i ^ j;
;         if (l > i) { if ((i & k) == 0 || k == 16) ce_desc(v[i], v[l]); else ce_desc(v[l], v[i]); }
;       }
; }
; DI void merge_top16(float (&v)[16], const float (&w)[16]) {
; #pragma unroll
;   for (int i = 0; i < 16; ++i) v[i] = fmaxf(v[i], w[15 - i]);
;   bitonic_merge16(v);
; DI void gemm256_tile(const Params& p, int mode, int layer, const u16* R, const u16* Cc, int brow, int bcol, lchar* shm, int tid_in, int wid) {
;     ...
;       if (kh == 0) {
;         float wk[16];
; #pragma unroll
;         for (int q = 0; q < 4; ++q) {
;           const f32x4 xv = *(const LAS f32x4*)((lchar*)S + tok * 80 + 16 * q);
;           wk[4 * q] = xv[0]; wk[4 * q + 1] = xv[1]; wk[4 * q + 2] = xv[2]; wk[4 * q + 3] = xv[3];
;         }
;         merge_top16(v, wk);
;       }
; #pragma unroll
;       for (int j = 0; j < 16; ++j) { if (ai == 0) L0[j] = v[j]; else L1[j] = v[j]; }
;     }
;     __syncthreads();
;     LAS unsigned* LL = (LAS unsigned*)shm;
;     if (kh == 0) {
; #pragma unroll
;       for (int j = 0; j < 16; ++j) { LL[tok * 32 + ((j + tok) & 31)] = __float_as_uint(L0[j]); LL[tok * 32 + ((16 + j + tok) & 31)] = __float_as_uint(L1[j]); }
.LBB0_233:
	s_and_b64 vcc, exec, s[4:5]
	s_waitcnt lgkmcnt(0)
	s_barrier
	s_cbranch_vccnz .LBB0_235
	ds_read_b128 v[168:171], v166 offset:48
	ds_read_b128 v[172:175], v166 offset:32
	ds_read_b128 v[178:181], v166
	ds_read_b128 v[182:185], v166 offset:16
	s_waitcnt lgkmcnt(3)
	v_max_f32_e32 v156, v156, v171
	v_max_f32_e32 v157, v157, v170
	v_max_f32_e32 v158, v158, v169
	v_max_f32_e32 v159, v159, v168
	s_waitcnt lgkmcnt(2)
	v_max_f32_e32 v152, v152, v175
	v_max_f32_e32 v153, v153, v174
	v_max_f32_e32 v154, v154, v173
	v_max_f32_e32 v155, v155, v172
	s_waitcnt lgkmcnt(0)
	v_max_f32_e32 v148, v148, v185
	v_max_f32_e32 v149, v149, v184
	v_max_f32_e32 v150, v150, v183
	v_max_f32_e32 v151, v151, v182
	v_max_f32_e32 v144, v144, v181
	v_max_f32_e32 v145, v145, v180
	v_max_f32_e32 v146, v146, v179
	v_max_f32_e32 v147, v147, v178
	v_max_f32_e32 v165, v156, v148
	v_min_f32_e32 v148, v156, v148
	v_max_f32_e32 v156, v157, v149
	v_min_f32_e32 v149, v157, v149
	v_max_f32_e32 v157, v158, v150
	v_min_f32_e32 v150, v158, v150
	v_max_f32_e32 v158, v159, v151
	v_min_f32_e32 v151, v159, v151
	v_max_f32_e32 v159, v152, v144
	v_min_f32_e32 v144, v152, v144
	v_max_f32_e32 v152, v153, v145
	v_min_f32_e32 v145, v153, v145
	v_max_f32_e32 v153, v154, v146
	v_min_f32_e32 v146, v154, v146
	v_max_f32_e32 v154, v155, v147
	v_min_f32_e32 v147, v155, v147
	v_max_f32_e32 v155, v165, v159
	v_min_f32_e32 v159, v165, v159
	v_max_f32_e32 v165, v156, v152
	v_min_f32_e32 v152, v156, v152
	v_max_f32_e32 v156, v157, v153
	v_min_f32_e32 v153, v157, v153
	v_max_f32_e32 v157, v158, v154
	v_min_f32_e32 v154, v158, v154
	v_max_f32_e32 v158, v148, v144
	v_min_f32_e32 v144, v148, v144
	v_max_f32_e32 v148, v149, v145
	v_min_f32_e32 v145, v149, v145
	v_max_f32_e32 v149, v150, v146
	v_min_f32_e32 v146, v150, v146
	v_max_f32_e32 v150, v151, v147
	v_min_f32_e32 v147, v151, v147
	v_max_f32_e32 v151, v155, v156
	v_min_f32_e32 v155, v155, v156
	v_max_f32_e32 v167, v165, v157
	v_min_f32_e32 v165, v165, v157
	v_max_f32_e32 v168, v159, v153
	v_min_f32_e32 v169, v159, v153
	v_max_f32_e32 v153, v152, v154
	v_min_f32_e32 v170, v152, v154
	v_max_f32_e32 v171, v158, v149
	v_min_f32_e32 v172, v158, v149
	v_max_f32_e32 v149, v148, v150
	v_min_f32_e32 v173, v148, v150
	v_max_f32_e32 v174, v144, v146
	v_min_f32_e32 v175, v144, v146
	v_max_f32_e32 v146, v145, v147
	v_min_f32_e32 v147, v145, v147
	v_max_f32_e32 v156, v151, v167
	v_min_f32_e32 v157, v151, v167
	v_max_f32_e32 v158, v155, v165
	v_min_f32_e32 v159, v155, v165
	v_max_f32_e32 v152, v168, v153
	v_min_f32_e32 v153, v168, v153
	v_max_f32_e32 v154, v169, v170
	v_min_f32_e32 v155, v169, v170
	v_max_f32_e32 v148, v171, v149
	v_min_f32_e32 v149, v171, v149
	v_max_f32_e32 v150, v172, v173
	v_min_f32_e32 v151, v172, v173
	v_max_f32_e32 v144, v174, v146
	v_min_f32_e32 v145, v174, v146
	v_max_f32_e32 v146, v175, v147
	v_min_f32_e32 v147, v175, v147
.LBB0_235:
	s_and_b64 vcc, exec, s[90:91]
	s_barrier
	s_cbranch_vccz .LBB0_237
	v_mad_u32_u24 v165, v164, 48, v166
	v_and_b32_e32 v167, 31, v163
	v_lshl_add_u32 v167, v167, 2, v165
	ds_write_b32 v167, v140
	v_bitop3_b32 v167, v163, 31, 16 bitop3:0x48
	v_lshl_add_u32 v167, v167, 2, v165
	ds_write_b32 v167, v156
	v_add_u32_e32 v167, 1, v163
	v_and_b32_e32 v167, 31, v167
	v_xor_b32_e32 v166, 16, v163
	v_lshl_add_u32 v167, v167, 2, v165
	ds_write_b32 v167, v141
	v_add_u32_e32 v167, 1, v166
	v_and_b32_e32 v167, 31, v167
	v_lshl_add_u32 v167, v167, 2, v165
	ds_write_b32 v167, v157
	v_add_u32_e32 v167, 2, v163
	v_and_b32_e32 v167, 31, v167
	v_lshl_add_u32 v167, v167, 2, v165
	ds_write_b32 v167, v142
	v_add_u32_e32 v167, 2, v166
	v_and_b32_e32 v167, 31, v167
	v_lshl_add_u32 v167, v167, 2, v165
	ds_write_b32 v167, v158
	v_add_u32_e32 v167, 3, v163
	v_and_b32_e32 v167, 31, v167
	v_lshl_add_u32 v167, v167, 2, v165
	ds_write_b32 v167, v143
	v_add_u32_e32 v167, 3, v166
	v_and_b32_e32 v167, 31, v167
	v_lshl_add_u32 v167, v167, 2, v165
	ds_write_b32 v167, v159
	v_add_u32_e32 v167, 4, v163
	v_and_b32_e32 v167, 31, v167
	v_lshl_add_u32 v167, v167, 2, v165
	ds_write_b32 v167, v136
	v_add_u32_e32 v167, 4, v166
	v_and_b32_e32 v167, 31, v167
	v_lshl_add_u32 v167, v167, 2, v165
	ds_write_b32 v167, v152
	v_add_u32_e32 v167, 5, v163
	v_and_b32_e32 v167, 31, v167
	v_lshl_add_u32 v167, v167, 2, v165
	ds_write_b32 v167, v137
	v_add_u32_e32 v167, 5, v166
	v_and_b32_e32 v167, 31, v167
	v_lshl_add_u32 v167, v167, 2, v165
	ds_write_b32 v167, v153
	v_add_u32_e32 v167, 6, v163
	v_and_b32_e32 v167, 31, v167
	v_lshl_add_u32 v167, v167, 2, v165
	ds_write_b32 v167, v138
	v_add_u32_e32 v167, 6, v166
	v_and_b32_e32 v167, 31, v167
	v_lshl_add_u32 v167, v167, 2, v165
	ds_write_b32 v167, v154
	v_add_u32_e32 v167, 7, v163
	v_and_b32_e32 v167, 31, v167
	v_lshl_add_u32 v167, v167, 2, v165
	ds_write_b32 v167, v139
	v_add_u32_e32 v167, 7, v166
	v_and_b32_e32 v167, 31, v167
	v_lshl_add_u32 v167, v167, 2, v165
	ds_write_b32 v167, v155
	v_add_u32_e32 v167, 8, v163
	v_and_b32_e32 v167, 31, v167
	v_lshl_add_u32 v167, v167, 2, v165
	ds_write_b32 v167, v132
	v_add_u32_e32 v167, 8, v166
	v_and_b32_e32 v167, 31, v167
	v_lshl_add_u32 v167, v167, 2, v165
	ds_write_b32 v167, v148
	v_add_u32_e32 v167, 9, v163
	v_and_b32_e32 v167, 31, v167
	v_lshl_add_u32 v167, v167, 2, v165
	ds_write_b32 v167, v133
	v_add_u32_e32 v167, 9, v166
	v_and_b32_e32 v167, 31, v167
	v_lshl_add_u32 v167, v167, 2, v165
	ds_write_b32 v167, v149
	v_add_u32_e32 v167, 10, v163
	v_and_b32_e32 v167, 31, v167
	v_lshl_add_u32 v167, v167, 2, v165
	ds_write_b32 v167, v134
	v_add_u32_e32 v167, 10, v166
	v_and_b32_e32 v167, 31, v167
	v_lshl_add_u32 v167, v167, 2, v165
	ds_write_b32 v167, v150
	v_add_u32_e32 v167, 11, v163
; DI void gemm256_tile(const Params& p, int mode, int layer, const u16* R, const u16* Cc, int brow, int bcol, lchar* shm, int tid_in, int wid) {
;     ...
;       for (int j = 0; j < 16; ++j) { LL[tok * 32 + ((j + tok) & 31)] = __float_as_uint(L0[j]); LL[tok * 32 + ((16 + j + tok) & 31)] = __float_as_uint(L1[j]); }
;       float s1[16], s2[16], v[16];
; #pragma unroll
;       for (int j = 0; j < 16; ++j) { s1[j] = __uint_as_float(__float_as_uint(L0[j]) & ~127u); s2[j] = __uint_as_float(__float_as_uint(L1[j]) & ~127u); v[j] = -3.0e38f; }
; #pragma unroll
;       for (int ch = 0; ch < 4; ++ch) {
;         float wk[16];
; #pragma unroll
;         for (int i = 0; i < 16; ++i) {
;           constexpr unsigned char PAIRS[64] = {0, 1, 2, 3, 4, 5, 6, 7, 8, 9, 10, 11, 12, 13, 14, 15, 16, 17, 18, 19, 20, 21, 22, 23, 32, 33, 34, 35, 36, 48, 49, 50, 51, 64, 65, 66, 80, 81, 96, 97, 112, 113, 128, 144, 160, 176, 192, 208, 224, 240, 255, 255, 255, 255, 255, 255, 255, 255, 255, 255, 255, 255, 255, 255};
;           const int code = PAIRS[ch * 16 + i];
;           if (code == 255) { wk[i] = -3.0e38f; }
;           else { const float sm = s1[code >> 4] + s2[code & 15]; wk[i] = __uint_as_float((__float_as_uint(sm) & ~255u) | (unsigned)code); }
;         }
;         if (ch == 0) {
; #pragma unroll
;           for (int i = 0; i < 16; ++i) v[i] = wk[i];
;         } else {
;           bitonic_sort16(wk);
;           merge_top16(v, wk);
;         }
	v_and_b32_e32 v167, 31, v167
	v_lshl_add_u32 v167, v167, 2, v165
	ds_write_b32 v167, v135
	v_add_u32_e32 v167, 11, v166
	v_and_b32_e32 v167, 31, v167
	v_lshl_add_u32 v167, v167, 2, v165
	ds_write_b32 v167, v151
	v_add_u32_e32 v167, 12, v163
	v_and_b32_e32 v167, 31, v167
	v_lshl_add_u32 v167, v167, 2, v165
	ds_write_b32 v167, v128
	v_add_u32_e32 v167, 12, v166
	v_and_b32_e32 v167, 31, v167
	v_lshl_add_u32 v167, v167, 2, v165
	ds_write_b32 v167, v144
	v_add_u32_e32 v167, 13, v163
	v_and_b32_e32 v167, 31, v167
	v_lshl_add_u32 v167, v167, 2, v165
	ds_write_b32 v167, v129
	v_add_u32_e32 v167, 13, v166
	v_and_b32_e32 v167, 31, v167
	v_lshl_add_u32 v167, v167, 2, v165
	ds_write_b32 v167, v145
	v_add_u32_e32 v167, 14, v163
	v_and_b32_e32 v167, 31, v167
	v_lshl_add_u32 v167, v167, 2, v165
	ds_write_b32 v167, v130
	v_add_u32_e32 v167, 14, v166
	v_and_b32_e32 v167, 31, v167
	v_lshl_add_u32 v167, v167, 2, v165
	ds_write_b32 v167, v146
	v_add_u32_e32 v167, 15, v163
	v_add_u32_e32 v166, 15, v166
	v_and_b32_e32 v167, 31, v167
	v_and_b32_e32 v166, 31, v166
	v_lshl_add_u32 v167, v167, 2, v165
	v_lshl_add_u32 v166, v166, 2, v165
	ds_write_b32 v167, v131
	ds_write_b32 v166, v147
	v_and_b32_e32 v166, 0xffffff80, v140
	v_and_b32_e32 v140, 0xffffff80, v156
	v_and_b32_e32 v141, 0xffffff80, v141
	v_and_b32_e32 v156, 0xffffff80, v157
	v_and_b32_e32 v157, 0xffffff80, v158
	v_and_b32_e32 v158, 0xffffff80, v159
	v_and_b32_e32 v152, 0xffffff80, v152
	v_and_b32_e32 v153, 0xffffff80, v153
	v_and_b32_e32 v154, 0xffffff80, v154
	v_and_b32_e32 v155, 0xffffff80, v155
	v_and_b32_e32 v148, 0xffffff80, v148
	v_and_b32_e32 v149, 0xffffff80, v149
	v_and_b32_e32 v150, 0xffffff80, v150
	v_and_b32_e32 v151, 0xffffff80, v151
	v_and_b32_e32 v159, 0xffffff80, v128
	v_and_b32_e32 v144, 0xffffff80, v144
	v_and_b32_e32 v167, 0xffffff80, v129
	v_and_b32_e32 v145, 0xffffff80, v145
	v_and_b32_e32 v129, 0xffffff80, v130
	v_and_b32_e32 v130, 0xffffff80, v146
	v_and_b32_e32 v128, 0xffffff80, v131
	v_and_b32_e32 v131, 0xffffff80, v147
	v_add_f32_e32 v146, v166, v140
	v_add_f32_e32 v147, v166, v156
	v_add_f32_e32 v168, v166, v157
	v_add_f32_e32 v169, v166, v158
	v_add_f32_e32 v170, v166, v152
	v_add_f32_e32 v171, v166, v153
	v_add_f32_e32 v172, v166, v154
	v_add_f32_e32 v173, v166, v155
	v_add_f32_e32 v148, v166, v148
	v_add_f32_e32 v149, v166, v149
	v_add_f32_e32 v150, v166, v150
	v_add_f32_e32 v151, v166, v151
	v_add_f32_e32 v144, v166, v144
	v_add_f32_e32 v145, v166, v145
	v_add_f32_e32 v130, v166, v130
	v_add_f32_e32 v131, v166, v131
	v_add_f32_e32 v166, v141, v140
	v_add_f32_e32 v174, v141, v156
	v_and_or_b32 v166, v166, s87, 16
	v_and_or_b32 v174, v174, s87, 17
	v_add_f32_e32 v175, v141, v157
	v_add_f32_e32 v176, v141, v158
	v_and_b32_e32 v142, 0xffffff80, v142
	v_and_or_b32 v175, v175, s87, 18
	v_and_or_b32 v176, v176, s87, 19
	v_add_f32_e32 v178, v141, v152
	v_add_f32_e32 v153, v141, v153
	v_add_f32_e32 v154, v141, v154
	v_add_f32_e32 v141, v141, v155
	v_and_b32_e32 v143, 0xffffff80, v143
	v_and_or_b32 v178, v178, s87, 20
	v_and_or_b32 v153, v153, s87, 21
	v_and_or_b32 v154, v154, s87, 22
	v_and_or_b32 v141, v141, s87, 23
	v_add_f32_e32 v155, v142, v140
	v_add_f32_e32 v179, v142, v156
	v_max_f32_e32 v184, v166, v174
	v_min_f32_e32 v166, v166, v174
	v_max_f32_e32 v174, v175, v175
	v_max_f32_e32 v175, v176, v176
	v_and_or_b32 v155, v155, s87, 32
	v_and_or_b32 v179, v179, s87, 33
	v_add_f32_e32 v180, v142, v157
	v_add_f32_e32 v181, v142, v158
	v_add_f32_e32 v142, v142, v152
	v_add_f32_e32 v152, v143, v140
	v_max_f32_e32 v176, v175, v174
	v_min_f32_e32 v174, v175, v174
	v_max_f32_e32 v175, v178, v178
	v_and_or_b32 v180, v180, s87, 34
	v_and_or_b32 v181, v181, s87, 35
	v_and_or_b32 v142, v142, s87, 36
	v_and_or_b32 v152, v152, s87, 48
	v_add_f32_e32 v182, v143, v156
	v_add_f32_e32 v183, v143, v157
	v_max_f32_e32 v178, v175, v153
	v_min_f32_e32 v153, v175, v153
	v_max_f32_e32 v175, v141, v154
	v_min_f32_e32 v141, v141, v154
	v_max_f32_e32 v154, v179, v179
	v_and_or_b32 v182, v182, s87, 49
	v_and_or_b32 v183, v183, s87, 50
	v_max_f32_e32 v179, v155, v154
	v_min_f32_e32 v154, v155, v154
	v_max_f32_e32 v155, v180, v180
	v_max_f32_e32 v180, v181, v181
	v_max_f32_e32 v181, v180, v155
	v_min_f32_e32 v155, v180, v155
	v_max_f32_e32 v180, v142, v152
	v_min_f32_e32 v142, v142, v152
	v_max_f32_e32 v152, v182, v182
	v_max_f32_e32 v182, v183, v183
	v_max_f32_e32 v183, v182, v152
	v_min_f32_e32 v152, v182, v152
	v_max_f32_e32 v182, v184, v174
	v_min_f32_e32 v174, v184, v174
	v_max_f32_e32 v184, v166, v176
	v_min_f32_e32 v166, v166, v176
	v_max_f32_e32 v176, v141, v178
	v_min_f32_e32 v141, v141, v178
	v_max_f32_e32 v178, v175, v153
	v_min_f32_e32 v153, v175, v153
	v_max_f32_e32 v175, v179, v155
	v_min_f32_e32 v155, v179, v155
	v_max_f32_e32 v179, v154, v181
	v_min_f32_e32 v154, v154, v181
	v_max_f32_e32 v181, v152, v180
	v_min_f32_e32 v152, v152, v180
	v_max_f32_e32 v180, v183, v142
	v_min_f32_e32 v142, v183, v142
	v_max_f32_e32 v183, v182, v184
	v_min_f32_e32 v182, v182, v184
	v_max_f32_e32 v184, v174, v166
	v_min_f32_e32 v166, v174, v166
	v_max_f32_e32 v174, v153, v141
	v_min_f32_e32 v141, v153, v141
	v_max_f32_e32 v153, v178, v176
	v_min_f32_e32 v176, v178, v176
	v_max_f32_e32 v178, v175, v179
	v_min_f32_e32 v175, v175, v179
	v_max_f32_e32 v179, v155, v154
	v_min_f32_e32 v154, v155, v154
	v_max_f32_e32 v155, v142, v152
	v_min_f32_e32 v142, v142, v152
	v_max_f32_e32 v152, v180, v181
	v_min_f32_e32 v180, v180, v181
	v_max_f32_e32 v181, v183, v141
	v_min_f32_e32 v141, v183, v141
	v_max_f32_e32 v183, v182, v174
	v_min_f32_e32 v174, v182, v174
	v_max_f32_e32 v182, v184, v176
	v_min_f32_e32 v176, v184, v176
; DI void ce_desc(float& hi, float& lo) { const float a = hi, b = lo; hi = fmaxf(a, b); lo = fminf(a, b); }
; DI void bitonic_sort16(float (&v)[16]) {
; #pragma unroll
;   for (int k = 2; k <= 16; k <<= 1)
; #pragma unroll
;     for (int j = k >> 1; j > 0; j >>= 1)
; #pragma unroll
;       for (int i = 0; i < 16; ++i) {
;         const int l = i ^ j;
;         if (l > i) { if ((i & k) == 0 || k == 16) ce_desc(v[i], v[l]); else ce_desc(v[l], v[i]); }
;       }
; }
; DI void merge_top16(float (&v)[16], const float (&w)[16]) {
; #pragma unroll
;   for (int i = 0; i < 16; ++i) v[i] = fmaxf(v[i], w[15 - i]);
;   bitonic_merge16(v);
; DI void gemm256_tile(const Params& p, int mode, int layer, const u16* R, const u16* Cc, int brow, int bcol, lchar* shm, int tid_in, int wid) {
;     ...
; #pragma unroll
;       for (int ch = 0; ch < 4; ++ch) {
;         float wk[16];
; #pragma unroll
;         for (int i = 0; i < 16; ++i) {
;           constexpr unsigned char PAIRS[64] = {0, 1, 2, 3, 4, 5, 6, 7, 8, 9, 10, 11, 12, 13, 14, 15, 16, 17, 18, 19, 20, 21, 22, 23, 32, 33, 34, 35, 36, 48, 49, 50, 51, 64, 65, 66, 80, 81, 96, 97, 112, 113, 128, 144, 160, 176, 192, 208, 224, 240, 255, 255, 255, 255, 255, 255, 255, 255, 255, 255, 255, 255, 255, 255};
;           const int code = PAIRS[ch * 16 + i];
;           if (code == 255) { wk[i] = -3.0e38f; }
;           else { const float sm = s1[code >> 4] + s2[code & 15]; wk[i] = __uint_as_float((__float_as_uint(sm) & ~255u) | (unsigned)code); }
;         }
;         if (ch == 0) {
; #pragma unroll
;           for (int i = 0; i < 16; ++i) v[i] = wk[i];
;         } else {
;           bitonic_sort16(wk);
;           merge_top16(v, wk);
;         }
	v_max_f32_e32 v184, v166, v153
	v_min_f32_e32 v153, v166, v153
	v_max_f32_e32 v166, v142, v178
	v_min_f32_e32 v142, v142, v178
	v_max_f32_e32 v178, v155, v175
	v_min_f32_e32 v155, v155, v175
	v_max_f32_e32 v175, v180, v179
	v_min_f32_e32 v179, v180, v179
	v_max_f32_e32 v180, v152, v154
	v_min_f32_e32 v152, v152, v154
	v_max_f32_e32 v154, v181, v182
	v_min_f32_e32 v181, v181, v182
	v_max_f32_e32 v182, v183, v184
	v_min_f32_e32 v183, v183, v184
	v_max_f32_e32 v184, v141, v176
	v_min_f32_e32 v141, v141, v176
	v_max_f32_e32 v176, v174, v153
	v_min_f32_e32 v153, v174, v153
	v_max_f32_e32 v174, v179, v142
	v_min_f32_e32 v142, v179, v142
	v_max_f32_e32 v179, v152, v155
	v_min_f32_e32 v152, v152, v155
	v_max_f32_e32 v155, v175, v166
	v_min_f32_e32 v166, v175, v166
	v_max_f32_e32 v175, v180, v178
	v_min_f32_e32 v178, v180, v178
	v_max_f32_e32 v180, v154, v182
	v_min_f32_e32 v154, v154, v182
	v_max_f32_e32 v182, v181, v183
	v_min_f32_e32 v181, v181, v183
	v_max_f32_e32 v183, v184, v176
	v_min_f32_e32 v176, v184, v176
	v_max_f32_e32 v184, v141, v153
	v_min_f32_e32 v141, v141, v153
	v_max_f32_e32 v153, v152, v142
	v_min_f32_e32 v142, v152, v142
	v_max_f32_e32 v152, v179, v174
	v_min_f32_e32 v174, v179, v174
	v_max_f32_e32 v179, v178, v166
	v_min_f32_e32 v166, v178, v166
	v_max_f32_e32 v178, v175, v155
	v_min_f32_e32 v155, v175, v155
	v_max_f32_e32 v175, v180, v142
	v_min_f32_e32 v142, v180, v142
	v_max_f32_e32 v180, v154, v153
	v_min_f32_e32 v153, v154, v153
	v_max_f32_e32 v154, v182, v174
	v_min_f32_e32 v174, v182, v174
	v_max_f32_e32 v182, v181, v152
	v_min_f32_e32 v152, v181, v152
	v_max_f32_e32 v181, v183, v166
	v_min_f32_e32 v166, v183, v166
	v_max_f32_e32 v183, v176, v179
	v_min_f32_e32 v176, v176, v179
	v_max_f32_e32 v179, v184, v155
	v_min_f32_e32 v155, v184, v155
	v_max_f32_e32 v184, v141, v178
	v_min_f32_e32 v141, v141, v178
	v_max_f32_e32 v178, v175, v181
	v_min_f32_e32 v175, v175, v181
	v_max_f32_e32 v181, v180, v183
	v_min_f32_e32 v180, v180, v183
	v_max_f32_e32 v183, v154, v179
	v_min_f32_e32 v154, v154, v179
	v_max_f32_e32 v179, v182, v184
	v_min_f32_e32 v182, v182, v184
	v_and_b32_e32 v136, 0xffffff80, v136
	v_and_b32_e32 v137, 0xffffff80, v137
	v_and_or_b32 v151, v151, s87, 11
	v_max_f32_e32 v184, v142, v166
	v_min_f32_e32 v142, v142, v166
	v_max_f32_e32 v166, v153, v176
	v_min_f32_e32 v153, v153, v176
	v_max_f32_e32 v176, v174, v155
	v_min_f32_e32 v155, v174, v155
	v_max_f32_e32 v174, v152, v141
	v_min_f32_e32 v141, v152, v141
	v_max_f32_e32 v152, v178, v183
	v_min_f32_e32 v178, v178, v183
	v_max_f32_e32 v183, v181, v179
	v_min_f32_e32 v179, v181, v179
	v_max_f32_e32 v181, v175, v154
	v_min_f32_e32 v154, v175, v154
	v_max_f32_e32 v175, v180, v182
	v_and_b32_e32 v138, 0xffffff80, v138
	v_and_or_b32 v171, v171, s87, 5
	v_min_f32_e32 v180, v180, v182
	v_max_f32_e32 v182, v184, v176
	v_min_f32_e32 v176, v184, v176
	v_max_f32_e32 v184, v166, v174
	v_min_f32_e32 v166, v166, v174
	v_min_f32_e32 v186, v181, v175
	v_max3_f32 v151, v151, v181, v175
	v_add_f32_e32 v143, v143, v158
	v_add_f32_e32 v158, v136, v140
	v_add_f32_e32 v175, v136, v156
	v_add_f32_e32 v136, v136, v157
	v_add_f32_e32 v157, v137, v140
	v_add_f32_e32 v137, v137, v156
	v_and_b32_e32 v139, 0xffffff80, v139
	v_and_b32_e32 v132, 0xffffff80, v132
	v_and_b32_e32 v133, 0xffffff80, v133
	v_and_or_b32 v145, v145, s87, 13
	v_min_f32_e32 v189, v176, v166
	v_max3_f32 v166, v171, v176, v166
	v_and_or_b32 v143, v143, s87, 51
	v_and_or_b32 v158, v158, s87, 64
	v_and_b32_e32 v175, 0xffffff00, v175
	v_and_b32_e32 v136, 0xffffff00, v136
	v_and_b32_e32 v157, 0xffffff00, v157
	v_and_b32_e32 v137, 0xffffff00, v137
	v_add_f32_e32 v176, v138, v140
	v_add_f32_e32 v138, v138, v156
	v_and_b32_e32 v134, 0xffffff80, v134
	v_and_b32_e32 v135, 0xffffff80, v135
	v_min_f32_e32 v185, v178, v179
	v_max3_f32 v145, v145, v178, v179
	v_or_b32_e32 v175, 0x41, v175
	v_or_b32_e32 v136, 0x42, v136
	v_or_b32_e32 v157, 0x50, v157
	v_or_b32_e32 v137, 0x51, v137
	v_and_b32_e32 v176, 0xffffff00, v176
	v_and_b32_e32 v138, 0xffffff00, v138
	v_add_f32_e32 v178, v139, v140
	v_add_f32_e32 v139, v139, v156
	v_add_f32_e32 v132, v132, v140
	v_add_f32_e32 v133, v133, v140
	v_or_b32_e32 v176, 0x60, v176
	v_or_b32_e32 v138, 0x61, v138
	v_and_b32_e32 v178, 0xffffff00, v178
	v_and_b32_e32 v139, 0xffffff00, v139
	v_and_b32_e32 v132, 0xffffff00, v132
	v_and_b32_e32 v133, 0xffffff00, v133
	v_add_f32_e32 v134, v134, v140
	v_add_f32_e32 v135, v135, v140
	v_add_f32_e32 v156, v159, v140
	v_add_f32_e32 v159, v167, v140
	v_max_f32_e32 v167, v143, v158
	v_min_f32_e32 v143, v143, v158
	v_max_f32_e32 v158, v175, v175
	v_or_b32_e32 v178, 0x70, v178
	v_or_b32_e32 v139, 0x71, v139
	v_or_b32_e32 v132, 0x80, v132
	v_or_b32_e32 v133, 0x90, v133
	v_and_b32_e32 v134, 0xffffff00, v134
	v_and_b32_e32 v135, 0xffffff00, v135
	v_max_f32_e32 v175, v136, v158
	v_min_f32_e32 v136, v136, v158
	v_max_f32_e32 v158, v157, v137
	v_min_f32_e32 v137, v157, v137
	v_max_f32_e32 v157, v176, v176
	v_or_b32_e32 v134, 0xa0, v134
	v_or_b32_e32 v135, 0xb0, v135
	v_and_b32_e32 v156, 0xffffff00, v156
	v_and_b32_e32 v159, 0xffffff00, v159
	v_max_f32_e32 v176, v138, v157
	v_min_f32_e32 v138, v138, v157
	v_max_f32_e32 v157, v178, v178
	v_or_b32_e32 v156, 0xc0, v156
	v_or_b32_e32 v159, 0xd0, v159
	v_max_f32_e32 v178, v157, v139
	v_min_f32_e32 v139, v157, v139
	v_max_f32_e32 v157, v133, v132
	v_min_f32_e32 v132, v133, v132
	v_max_f32_e32 v133, v135, v135
	v_max_f32_e32 v135, v134, v133
	v_min_f32_e32 v133, v134, v133
	v_max_f32_e32 v134, v156, v156
	v_max_f32_e32 v156, v159, v159
	v_max_f32_e32 v159, v156, v134
	v_min_f32_e32 v134, v156, v134
	v_max_f32_e32 v156, v167, v136
; DI void ce_desc(float& hi, float& lo) { const float a = hi, b = lo; hi = fmaxf(a, b); lo = fminf(a, b); }
; DI void bitonic_sort16(float (&v)[16]) {
; #pragma unroll
;   for (int k = 2; k <= 16; k <<= 1)
; #pragma unroll
;     for (int j = k >> 1; j > 0; j >>= 1)
; #pragma unroll
;       for (int i = 0; i < 16; ++i) {
;         const int l = i ^ j;
;         if (l > i) { if ((i & k) == 0 || k == 16) ce_desc(v[i], v[l]); else ce_desc(v[l], v[i]); }
;       }
; }
; DI void merge_top16(float (&v)[16], const float (&w)[16]) {
; #pragma unroll
;   for (int i = 0; i < 16; ++i) v[i] = fmaxf(v[i], w[15 - i]);
;   bitonic_merge16(v);
; DI void gemm256_tile(const Params& p, int mode, int layer, const u16* R, const u16* Cc, int brow, int bcol, lchar* shm, int tid_in, int wid) {
;     ...
; #pragma unroll
;       for (int ch = 0; ch < 4; ++ch) {
;         float wk[16];
; #pragma unroll
;         for (int i = 0; i < 16; ++i) {
;           constexpr unsigned char PAIRS[64] = {0, 1, 2, 3, 4, 5, 6, 7, 8, 9, 10, 11, 12, 13, 14, 15, 16, 17, 18, 19, 20, 21, 22, 23, 32, 33, 34, 35, 36, 48, 49, 50, 51, 64, 65, 66, 80, 81, 96, 97, 112, 113, 128, 144, 160, 176, 192, 208, 224, 240, 255, 255, 255, 255, 255, 255, 255, 255, 255, 255, 255, 255, 255, 255};
;           const int code = PAIRS[ch * 16 + i];
;           if (code == 255) { wk[i] = -3.0e38f; }
;           else { const float sm = s1[code >> 4] + s2[code & 15]; wk[i] = __uint_as_float((__float_as_uint(sm) & ~255u) | (unsigned)code); }
;         }
;         if (ch == 0) {
; #pragma unroll
;           for (int i = 0; i < 16; ++i) v[i] = wk[i];
;         } else {
;           bitonic_sort16(wk);
;           merge_top16(v, wk);
;         }
	v_min_f32_e32 v136, v167, v136
	v_max_f32_e32 v167, v143, v175
	v_min_f32_e32 v143, v143, v175
	v_max_f32_e32 v175, v138, v158
	v_min_f32_e32 v138, v138, v158
	v_max_f32_e32 v158, v176, v137
	v_min_f32_e32 v137, v176, v137
	v_max_f32_e32 v176, v178, v132
	v_min_f32_e32 v132, v178, v132
	v_max_f32_e32 v178, v139, v157
	v_min_f32_e32 v139, v139, v157
	v_max_f32_e32 v157, v134, v135
	v_min_f32_e32 v134, v134, v135
	v_max_f32_e32 v135, v159, v133
	v_min_f32_e32 v133, v159, v133
	v_max_f32_e32 v159, v156, v167
	v_min_f32_e32 v156, v156, v167
	v_max_f32_e32 v167, v136, v143
	v_min_f32_e32 v136, v136, v143
	v_max_f32_e32 v143, v137, v138
	v_min_f32_e32 v137, v137, v138
	v_max_f32_e32 v138, v158, v175
	v_min_f32_e32 v158, v158, v175
	v_max_f32_e32 v175, v176, v178
	v_min_f32_e32 v176, v176, v178
	v_max_f32_e32 v178, v132, v139
	v_min_f32_e32 v132, v132, v139
	v_max_f32_e32 v139, v133, v134
	v_min_f32_e32 v133, v133, v134
	v_max_f32_e32 v134, v135, v157
	v_min_f32_e32 v135, v135, v157
	v_and_b32_e32 v146, 0xffffff00, v146
	v_and_or_b32 v147, v147, s87, 1
	v_and_or_b32 v168, v168, s87, 2
	v_and_or_b32 v169, v169, s87, 3
	v_and_or_b32 v170, v170, s87, 4
	v_and_or_b32 v172, v172, s87, 6
	v_and_or_b32 v148, v148, s87, 8
	v_and_or_b32 v150, v150, s87, 10
	v_and_or_b32 v144, v144, s87, 12
	v_and_or_b32 v130, v130, s87, 14
	v_max_f32_e32 v174, v142, v155
	v_min_f32_e32 v142, v142, v155
	v_max_f32_e32 v155, v153, v141
	v_min_f32_e32 v141, v153, v141
	v_max_f32_e32 v157, v159, v137
	v_min_f32_e32 v137, v159, v137
	v_max_f32_e32 v159, v156, v143
	v_min_f32_e32 v143, v156, v143
	v_max_f32_e32 v156, v167, v158
	v_min_f32_e32 v158, v167, v158
	v_max_f32_e32 v167, v136, v138
	v_min_f32_e32 v136, v136, v138
	v_max_f32_e32 v138, v133, v175
	v_min_f32_e32 v133, v133, v175
	v_max_f32_e32 v175, v139, v176
	v_min_f32_e32 v139, v139, v176
	v_max_f32_e32 v176, v135, v178
	v_min_f32_e32 v135, v135, v178
	v_max_f32_e32 v178, v134, v132
	v_min_f32_e32 v132, v134, v132
	v_and_or_b32 v173, v173, s87, 7
	v_and_or_b32 v149, v149, s87, 9
	v_and_or_b32 v131, v131, s87, 15
	v_min_f32_e32 v153, v152, v183
	v_min_f32_e32 v187, v154, v180
	v_min_f32_e32 v188, v182, v184
	v_min_f32_e32 v190, v174, v155
	v_min_f32_e32 v191, v142, v141
	v_max3_f32 v141, v147, v142, v141
	v_max_f32_e32 v142, v168, v168
	v_max3_f32 v147, v169, v174, v155
	v_max_f32_e32 v134, v157, v156
	v_min_f32_e32 v156, v157, v156
	v_max_f32_e32 v157, v159, v167
	v_min_f32_e32 v159, v159, v167
	v_max_f32_e32 v167, v137, v158
	v_min_f32_e32 v137, v137, v158
	v_max_f32_e32 v158, v143, v136
	v_min_f32_e32 v136, v143, v136
	v_max_f32_e32 v143, v135, v133
	v_min_f32_e32 v133, v135, v133
	v_max_f32_e32 v135, v132, v139
	v_min_f32_e32 v132, v132, v139
	v_max_f32_e32 v139, v176, v138
	v_min_f32_e32 v138, v176, v138
	v_max_f32_e32 v176, v178, v175
	v_min_f32_e32 v175, v178, v175
	v_max_f32_e32 v146, v146, v191
	v_max_f32_e32 v142, v142, v190
	v_max_f32_e32 v155, v170, v189
	v_max_f32_e32 v168, v172, v188
	v_max3_f32 v169, v173, v182, v184
	v_max_f32_e32 v148, v148, v187
	v_max3_f32 v149, v149, v154, v180
	v_max_f32_e32 v150, v150, v186
	v_max_f32_e32 v144, v144, v185
	v_max_f32_e32 v130, v130, v153
	v_max3_f32 v131, v131, v152, v183
	v_max_f32_e32 v178, v134, v157
	v_min_f32_e32 v134, v134, v157
	v_max_f32_e32 v157, v156, v159
	v_min_f32_e32 v156, v156, v159
	v_max_f32_e32 v159, v167, v158
	v_min_f32_e32 v158, v167, v158
	v_max_f32_e32 v167, v137, v136
	v_min_f32_e32 v136, v137, v136
	v_max_f32_e32 v137, v132, v133
	v_min_f32_e32 v132, v132, v133
	v_max_f32_e32 v133, v135, v143
	v_min_f32_e32 v135, v135, v143
	v_max_f32_e32 v143, v175, v138
	v_min_f32_e32 v138, v175, v138
	v_max_f32_e32 v175, v176, v139
	v_min_f32_e32 v139, v176, v139
	v_add_f32_e32 v129, v129, v140
	v_add_f32_e32 v128, v128, v140
	v_max_f32_e32 v152, v146, v148
	v_min_f32_e32 v146, v146, v148
	v_max_f32_e32 v148, v141, v149
	v_min_f32_e32 v141, v141, v149
	v_max_f32_e32 v149, v142, v150
	v_min_f32_e32 v142, v142, v150
	v_max_f32_e32 v150, v147, v151
	v_min_f32_e32 v147, v147, v151
	v_max_f32_e32 v151, v155, v144
	v_min_f32_e32 v144, v155, v144
	v_max_f32_e32 v153, v166, v145
	v_max_f32_e32 v154, v168, v130
	v_max_f32_e32 v155, v169, v131
	v_max_f32_e32 v176, v178, v132
	v_min_f32_e32 v132, v178, v132
	v_max_f32_e32 v178, v134, v137
	v_min_f32_e32 v134, v134, v137
	v_max_f32_e32 v137, v157, v135
	v_min_f32_e32 v135, v157, v135
	v_max_f32_e32 v157, v156, v133
	v_min_f32_e32 v133, v156, v133
	v_max_f32_e32 v156, v159, v138
	v_min_f32_e32 v138, v159, v138
	v_max_f32_e32 v159, v158, v143
	v_min_f32_e32 v143, v158, v143
	v_max_f32_e32 v158, v167, v139
	v_min_f32_e32 v139, v167, v139
	v_max_f32_e32 v167, v136, v175
	v_min_f32_e32 v136, v136, v175
	v_and_b32_e32 v129, 0xffffff00, v129
	v_and_b32_e32 v128, 0xffffff00, v128
	v_min_f32_e32 v145, v166, v145
	v_min_f32_e32 v130, v168, v130
	v_min_f32_e32 v131, v169, v131
	v_max_f32_e32 v166, v152, v151
	v_min_f32_e32 v151, v152, v151
	v_max_f32_e32 v152, v148, v153
	v_min_f32_e32 v148, v148, v153
	v_max_f32_e32 v153, v149, v154
	v_min_f32_e32 v149, v149, v154
	v_max_f32_e32 v154, v150, v155
	v_max_f32_e32 v175, v176, v156
	v_min_f32_e32 v156, v176, v156
	v_max_f32_e32 v176, v178, v159
	v_min_f32_e32 v159, v178, v159
	v_max_f32_e32 v178, v137, v158
	v_min_f32_e32 v137, v137, v158
	v_max_f32_e32 v158, v157, v167
	v_min_f32_e32 v157, v157, v167
	v_max_f32_e32 v167, v132, v138
	v_min_f32_e32 v132, v132, v138
	v_max_f32_e32 v138, v134, v143
	v_min_f32_e32 v134, v134, v143
	v_max_f32_e32 v143, v135, v139
	v_min_f32_e32 v135, v135, v139
	v_max_f32_e32 v139, v133, v136
	v_or_b32_e32 v129, 0xe0, v129
	v_or_b32_e32 v128, 0xf0, v128
; DI void merge_top16(float (&v)[16], const float (&w)[16]) {
; #pragma unroll
;   for (int i = 0; i < 16; ++i) v[i] = fmaxf(v[i], w[15 - i]);
;   bitonic_merge16(v);
; DI void gemm256_tile(const Params& p, int mode, int layer, const u16* R, const u16* Cc, int brow, int bcol, lchar* shm, int tid_in, int wid) {
;     ...
; #pragma unroll
;       for (int ch = 0; ch < 4; ++ch) {
;         float wk[16];
; #pragma unroll
;         for (int i = 0; i < 16; ++i) {
;           constexpr unsigned char PAIRS[64] = {0, 1, 2, 3, 4, 5, 6, 7, 8, 9, 10, 11, 12, 13, 14, 15, 16, 17, 18, 19, 20, 21, 22, 23, 32, 33, 34, 35, 36, 48, 49, 50, 51, 64, 65, 66, 80, 81, 96, 97, 112, 113, 128, 144, 160, 176, 192, 208, 224, 240, 255, 255, 255, 255, 255, 255, 255, 255, 255, 255, 255, 255, 255, 255};
;           const int code = PAIRS[ch * 16 + i];
;           if (code == 255) { wk[i] = -3.0e38f; }
;           else { const float sm = s1[code >> 4] + s2[code & 15]; wk[i] = __uint_as_float((__float_as_uint(sm) & ~255u) | (unsigned)code); }
;         }
;         if (ch == 0) {
; #pragma unroll
;           for (int i = 0; i < 16; ++i) v[i] = wk[i];
;         } else {
;           bitonic_sort16(wk);
;           merge_top16(v, wk);
;         }
	v_min_f32_e32 v150, v150, v155
	v_max_f32_e32 v155, v146, v144
	v_min_f32_e32 v144, v146, v144
	v_max_f32_e32 v146, v141, v145
	v_min_f32_e32 v141, v141, v145
	v_max_f32_e32 v145, v142, v130
	v_min_f32_e32 v130, v142, v130
	v_max_f32_e32 v142, v147, v131
	v_min_f32_e32 v131, v147, v131
	v_max_f32_e32 v147, v166, v153
	v_min_f32_e32 v153, v166, v153
	v_max_f32_e32 v166, v152, v154
	v_min_f32_e32 v133, v133, v136
	v_max_f32_e32 v136, v175, v178
	v_min_f32_e32 v175, v175, v178
	v_max_f32_e32 v178, v176, v158
	v_min_f32_e32 v158, v176, v158
	v_max_f32_e32 v176, v156, v137
	v_min_f32_e32 v137, v156, v137
	v_max_f32_e32 v156, v159, v157
	v_min_f32_e32 v157, v159, v157
	v_max_f32_e32 v159, v167, v143
	v_min_f32_e32 v143, v167, v143
	v_max_f32_e32 v167, v138, v139
	v_min_f32_e32 v152, v152, v154
	v_max_f32_e32 v154, v151, v149
	v_min_f32_e32 v149, v151, v149
	v_max_f32_e32 v151, v148, v150
	v_min_f32_e32 v148, v148, v150
	v_max_f32_e32 v150, v155, v145
	v_min_f32_e32 v145, v155, v145
	v_max_f32_e32 v155, v146, v142
	v_min_f32_e32 v142, v146, v142
	v_max_f32_e32 v146, v144, v130
	v_min_f32_e32 v130, v144, v130
	v_max_f32_e32 v144, v141, v131
	v_min_f32_e32 v131, v141, v131
	v_min_f32_e32 v141, v147, v166
	v_min_f32_e32 v138, v138, v139
	v_max_f32_e32 v139, v132, v135
	v_min_f32_e32 v132, v132, v135
	v_max_f32_e32 v135, v134, v133
	v_min_f32_e32 v133, v134, v133
	v_min_f32_e32 v181, v137, v157
	v_min_f32_e32 v182, v159, v167
	v_max_f32_e32 v140, v129, v128
	v_min_f32_e32 v128, v129, v128
	v_min_f32_e32 v170, v149, v148
	v_min_f32_e32 v171, v150, v155
	v_min_f32_e32 v172, v145, v142
	v_min_f32_e32 v173, v146, v144
	v_min_f32_e32 v179, v175, v158
	v_min_f32_e32 v180, v176, v156
	v_min_f32_e32 v185, v132, v133
	v_max3_f32 v132, v141, v132, v133
	v_max3_f32 v141, v149, v148, v182
	v_max3_f32 v148, v150, v155, v181
	v_max_f32_e32 v155, 0xff61b1e6, v140
	v_max_f32_e32 v129, 0xff61b1e6, v128
	v_min_f32_e32 v140, 0xff61b1e6, v140
	v_min_f32_e32 v128, 0xff61b1e6, v128
	v_min_f32_e32 v169, v154, v151
	v_max3_f32 v142, v145, v142, v180
	v_max3_f32 v145, v172, v176, v156
	v_max3_f32 v144, v146, v144, v179
	v_max3_f32 v146, v173, v175, v158
	v_max_f32_e32 v156, v155, v129
	v_max_f32_e32 v158, v140, v128
	v_min_f32_e32 v129, v155, v129
	v_min_f32_e32 v128, v140, v128
	v_min_f32_e32 v183, v143, v138
	v_max3_f32 v138, v169, v143, v138
	v_max3_f32 v143, v170, v159, v167
	v_max3_f32 v137, v171, v137, v157
	v_max_f32_e32 v157, 0xff61b1e6, v156
	v_max_f32_e32 v159, 0xff61b1e6, v158
	v_max_f32_e32 v155, 0xff61b1e6, v129
	v_max_f32_e32 v140, 0xff61b1e6, v128
	v_min_f32_e32 v156, 0xff61b1e6, v156
	v_min_f32_e32 v158, 0xff61b1e6, v158
	v_min_f32_e32 v129, 0xff61b1e6, v129
	v_min_f32_e32 v128, 0xff61b1e6, v128
	v_min_f32_e32 v168, v153, v152
	v_max3_f32 v147, v147, v166, v185
	v_max_f32_e32 v166, v157, v159
	v_max_f32_e32 v167, v155, v140
	v_max_f32_e32 v170, v156, v158
	v_max_f32_e32 v171, v129, v128
	v_min_f32_e32 v157, v157, v159
	v_min_f32_e32 v140, v155, v140
	v_min_f32_e32 v156, v156, v158
	v_min_f32_e32 v128, v129, v128
	v_min_f32_e32 v174, v130, v131
	v_min_f32_e32 v134, v136, v178
	v_min_f32_e32 v184, v139, v135
	v_max3_f32 v135, v168, v139, v135
	v_max_f32_e32 v168, v166, v167
	v_max_f32_e32 v172, v170, v171
	v_max_f32_e32 v155, v157, v140
	v_max_f32_e32 v129, v156, v128
	v_min_f32_e32 v166, v166, v167
	v_min_f32_e32 v170, v170, v171
	v_min_f32_e32 v140, v157, v140
	v_min_f32_e32 v128, v156, v128
	v_max3_f32 v133, v153, v152, v184
	v_max3_f32 v139, v154, v151, v183
	v_max3_f32 v130, v130, v131, v134
	v_max3_f32 v131, v174, v136, v178
	v_min_f32_e32 v169, 0xff61b1e6, v168
	v_min_f32_e32 v173, 0xff61b1e6, v172
	v_min_f32_e32 v159, 0xff61b1e6, v155
	v_min_f32_e32 v158, 0xff61b1e6, v129
	v_min_f32_e32 v167, 0xff61b1e6, v166
	v_min_f32_e32 v171, 0xff61b1e6, v170
	v_min_f32_e32 v157, 0xff61b1e6, v140
	v_min_f32_e32 v156, 0xff61b1e6, v128
	v_max_f32_e32 v134, v147, v148
	v_min_f32_e32 v136, v147, v148
	v_max_f32_e32 v147, v132, v137
	v_min_f32_e32 v132, v132, v137
	v_max_f32_e32 v137, v133, v142
	v_min_f32_e32 v133, v133, v142
	v_max_f32_e32 v142, v135, v145
	v_min_f32_e32 v135, v135, v145
	v_max_f32_e32 v145, v139, v144
	v_min_f32_e32 v139, v139, v144
	v_max_f32_e32 v144, v138, v146
	v_min_f32_e32 v138, v138, v146
	v_max_f32_e32 v146, v141, v130
	v_min_f32_e32 v130, v141, v130
	v_max_f32_e32 v141, v143, v131
	v_min_f32_e32 v174, v169, v173
	v_min_f32_e32 v175, v159, v158
	v_min_f32_e32 v178, v167, v171
	v_min_f32_e32 v179, v157, v156
	v_min_f32_e32 v131, v143, v131
	v_max_f32_e32 v143, v134, v145
	v_min_f32_e32 v134, v134, v145
	v_max_f32_e32 v145, v147, v144
	v_min_f32_e32 v144, v147, v144
	v_max_f32_e32 v147, v137, v146
	v_min_f32_e32 v137, v137, v146
	v_max_f32_e32 v146, v142, v141
	v_min_f32_e32 v176, v174, v175
	v_min_f32_e32 v180, v178, v179
	v_max_f32_e32 v169, v169, v173
	v_max_f32_e32 v158, v159, v158
	v_max_f32_e32 v167, v167, v171
	v_max_f32_e32 v156, v157, v156
	v_min_f32_e32 v141, v142, v141
	v_max_f32_e32 v142, v136, v139
	v_min_f32_e32 v136, v136, v139
	v_max_f32_e32 v139, v132, v138
	v_min_f32_e32 v132, v132, v138
	v_max_f32_e32 v138, v133, v130
	v_min_f32_e32 v130, v133, v130
	v_max_f32_e32 v133, v135, v131
	v_min_f32_e32 v131, v135, v131
	v_max_f32_e32 v135, v143, v147
	v_min_f32_e32 v143, v143, v147
	v_max_f32_e32 v147, v145, v146
	v_min_f32_e32 v181, v176, v180
	v_min_f32_e32 v159, v169, v158
	v_min_f32_e32 v157, v167, v156
	v_min_f32_e32 v145, v145, v146
	v_max_f32_e32 v146, v134, v137
	v_min_f32_e32 v134, v134, v137
	v_max_f32_e32 v137, v144, v141
	v_min_f32_e32 v141, v144, v141
	v_max_f32_e32 v144, v142, v138
	v_min_f32_e32 v138, v142, v138
; DI float fast_exp2(float x) { return __builtin_amdgcn_exp2f(x); }
; DI void gemm256_tile(const Params& p, int mode, int layer, const u16* R, const u16* Cc, int brow, int bcol, lchar* shm, int tid_in, int wid) {
;     ...
;         if (ch == 0) {
; #pragma unroll
;           for (int i = 0; i < 16; ++i) v[i] = wk[i];
;         } else {
;           bitonic_sort16(wk);
;           merge_top16(v, wk);
;         }
;       }
;       float e[16], sum = 0.f;
;       const float mx = __uint_as_float(__float_as_uint(v[0]) & ~255u);
; #pragma unroll
;       for (int j = 0; j < 16; ++j) { e[j] = fast_exp2((__uint_as_float(__float_as_uint(v[j]) & ~255u) - mx) * LOG2E); sum += e[j]; }
	v_max_f32_e32 v142, v139, v133
	v_min_f32_e32 v133, v139, v133
	v_max_f32_e32 v139, v136, v130
	v_min_f32_e32 v130, v136, v130
	v_max_f32_e32 v136, v132, v131
	v_min_f32_e32 v131, v132, v131
	v_min_f32_e32 v132, v135, v147
	v_max3_f32 v135, v135, v147, v181
	v_max_f32_e32 v147, 0xff61b1e6, v168
	v_max_f32_e32 v168, 0xff61b1e6, v172
	v_max_f32_e32 v155, 0xff61b1e6, v155
	v_max_f32_e32 v129, 0xff61b1e6, v129
	v_max_f32_e32 v166, 0xff61b1e6, v166
	v_max_f32_e32 v170, 0xff61b1e6, v170
	v_min_f32_e32 v171, v159, v157
	v_min_f32_e32 v149, v146, v137
	v_min_f32_e32 v172, v147, v168
	v_min_f32_e32 v181, v155, v129
	v_min_f32_e32 v183, v166, v170
	v_max_f32_e32 v140, 0xff61b1e6, v140
	v_max_f32_e32 v128, 0xff61b1e6, v128
	v_max3_f32 v137, v146, v137, v171
	v_max_f32_e32 v146, v147, v168
	v_max_f32_e32 v129, v155, v129
	v_max_f32_e32 v155, v166, v170
	v_max_f32_e32 v168, v174, v175
	v_max_f32_e32 v170, v178, v179
	v_min_f32_e32 v184, v140, v128
	v_max_f32_e32 v128, v140, v128
	v_min_f32_e32 v171, v168, v170
	v_max_f32_e32 v158, v169, v158
	v_max_f32_e32 v156, v167, v156
	v_min_f32_e32 v148, v143, v145
	v_min_f32_e32 v182, v172, v181
	v_min_f32_e32 v185, v183, v184
	v_min_f32_e32 v147, v146, v129
	v_min_f32_e32 v140, v155, v128
	v_max3_f32 v143, v143, v145, v171
	v_max_f32_e32 v145, v172, v181
	v_max_f32_e32 v171, v183, v184
	v_min_f32_e32 v167, v158, v156
	v_max_f32_e32 v129, v146, v129
	v_max_f32_e32 v128, v155, v128
	v_min_f32_e32 v150, v134, v141
	v_min_f32_e32 v151, v144, v142
	v_min_f32_e32 v152, v138, v133
	v_min_f32_e32 v153, v139, v136
	v_min_f32_e32 v154, v130, v131
	v_min_f32_e32 v186, v182, v185
	v_min_f32_e32 v166, v147, v140
	v_min_f32_e32 v172, v145, v171
	v_max3_f32 v134, v134, v141, v167
	v_min_f32_e32 v141, v129, v128
	v_max3_f32 v142, v144, v142, v186
	v_max3_f32 v136, v139, v136, v166
	v_max3_f32 v133, v138, v133, v172
	v_max3_f32 v130, v130, v131, v141
	v_max3_f32 v132, v132, v176, v180
	v_max3_f32 v151, v151, v182, v185
	v_max3_f32 v149, v149, v159, v157
	v_max3_f32 v140, v153, v147, v140
	v_max3_f32 v148, v148, v168, v170
	v_max3_f32 v145, v152, v145, v171
	v_max3_f32 v150, v150, v158, v156
	v_max3_f32 v128, v154, v129, v128
	v_min_f32_e32 v144, v135, v142
	v_min_f32_e32 v139, v137, v136
	v_min_f32_e32 v138, v143, v133
	v_min_f32_e32 v131, v134, v130
	v_min_f32_e32 v155, v132, v151
	v_min_f32_e32 v147, v149, v140
	v_min_f32_e32 v152, v148, v145
	v_min_f32_e32 v129, v150, v128
	v_min_f32_e32 v166, v144, v139
	v_min_f32_e32 v141, v138, v131
	v_min_f32_e32 v153, v155, v147
	v_min_f32_e32 v154, v152, v129
	v_min_f32_e32 v146, v166, v141
	v_min_f32_e32 v156, v153, v154
	v_min_f32_e32 v157, v146, v156
	v_max_f32_e32 v156, v146, v156
	v_max_f32_e32 v141, v166, v141
	v_max_f32_e32 v146, v153, v154
	v_min_f32_e32 v153, v141, v146
	v_max_f32_e32 v154, v141, v146
	v_max_f32_e32 v139, v144, v139
	v_max_f32_e32 v131, v138, v131
	v_max_f32_e32 v141, v155, v147
	v_max_f32_e32 v129, v152, v129
	v_min_f32_e32 v138, v139, v131
	v_min_f32_e32 v144, v141, v129
	v_max_f32_e32 v131, v139, v131
	v_max_f32_e32 v129, v141, v129
	v_min_f32_e32 v158, v131, v129
	v_max_f32_e32 v159, v131, v129
	v_max_f32_e32 v129, v135, v142
	v_max_f32_e32 v131, v137, v136
	v_max_f32_e32 v133, v143, v133
	v_max_f32_e32 v130, v134, v130
	v_max_f32_e32 v132, v132, v151
	v_max_f32_e32 v137, v149, v140
	v_max_f32_e32 v139, v148, v145
	v_max_f32_e32 v128, v150, v128
	v_min_f32_e32 v152, v138, v144
	v_max_f32_e32 v155, v138, v144
	v_min_f32_e32 v135, v129, v131
	v_min_f32_e32 v134, v133, v130
	v_min_f32_e32 v138, v132, v137
	v_min_f32_e32 v140, v139, v128
	v_max_f32_e32 v129, v129, v131
	v_max_f32_e32 v130, v133, v130
	v_max_f32_e32 v132, v132, v137
	v_max_f32_e32 v128, v139, v128
	v_min_f32_e32 v131, v129, v130
	v_min_f32_e32 v133, v132, v128
	v_max_f32_e32 v129, v129, v130
	v_max_f32_e32 v128, v132, v128
	v_max_f32_e32 v169, v129, v128
	v_max_f32_e32 v167, v131, v133
	v_min_f32_e32 v168, v129, v128
	v_and_b32_e32 v145, 0xffffff00, v169
	v_and_b32_e32 v129, 0xffffff00, v168
	v_and_b32_e32 v130, 0xffffff00, v167
	v_sub_f32_e32 v128, v145, v145
	v_min_f32_e32 v166, v131, v133
	v_mul_f32_e32 v128, 0x3fb8aa3b, v128
	v_sub_f32_e32 v129, v129, v145
	v_sub_f32_e32 v130, v130, v145
	v_and_b32_e32 v131, 0xffffff00, v166
	v_exp_f32_e32 v128, v128
	v_mul_f32_e32 v129, 0x3fb8aa3b, v129
	v_mul_f32_e32 v130, 0x3fb8aa3b, v130
	v_exp_f32_e32 v129, v129
	v_exp_f32_e32 v132, v130
	v_sub_f32_e32 v130, v131, v145
	v_mul_f32_e32 v130, 0x3fb8aa3b, v130
	v_exp_f32_e32 v133, v130
	v_min_f32_e32 v136, v135, v134
	v_max_f32_e32 v134, v135, v134
	v_max_f32_e32 v135, v138, v140
	v_add_f32_e32 v130, 0, v128
	v_min_f32_e32 v141, v138, v140
	v_max_f32_e32 v151, v134, v135
	v_add_f32_e32 v130, v129, v130
	v_max_f32_e32 v149, v136, v141
	v_min_f32_e32 v150, v134, v135
	v_and_b32_e32 v134, 0xffffff00, v151
	v_add_f32_e32 v130, v132, v130
	v_min_f32_e32 v148, v136, v141
	v_and_b32_e32 v135, 0xffffff00, v150
	v_and_b32_e32 v136, 0xffffff00, v149
	v_add_f32_e32 v147, v133, v130
	v_sub_f32_e32 v130, v134, v145
	v_mul_f32_e32 v130, 0x3fb8aa3b, v130
	v_sub_f32_e32 v131, v135, v145
	v_sub_f32_e32 v134, v136, v145
	v_and_b32_e32 v137, 0xffffff00, v148
	v_exp_f32_e32 v130, v130
	v_mul_f32_e32 v131, 0x3fb8aa3b, v131
	v_mul_f32_e32 v134, 0x3fb8aa3b, v134
	v_exp_f32_e32 v131, v131
	v_exp_f32_e32 v136, v134
	v_sub_f32_e32 v134, v137, v145
	v_mul_f32_e32 v134, 0x3fb8aa3b, v134
	v_exp_f32_e32 v137, v134
	v_add_f32_e32 v134, v130, v147
	v_add_f32_e32 v134, v131, v134
	v_and_b32_e32 v138, 0xffffff00, v159
	v_add_f32_e32 v134, v136, v134
	v_and_b32_e32 v139, 0xffffff00, v158
	v_and_b32_e32 v140, 0xffffff00, v155
; DI float fast_exp2(float x) { return __builtin_amdgcn_exp2f(x); }
; DI void gemm256_tile(const Params& p, int mode, int layer, const u16* R, const u16* Cc, int brow, int bcol, lchar* shm, int tid_in, int wid) {
;     ...
;       for (int j = 0; j < 16; ++j) { e[j] = fast_exp2((__uint_as_float(__float_as_uint(v[j]) & ~255u) - mx) * LOG2E); sum += e[j]; }
;       const float inv = 1.0f / sum;
;       const int hd = brow >> 8;
;       u16* di = W_IDX(p) + (size_t)(bcol + tok) * 128 + hd * 16;
;       float* dg = W_G(p) + (size_t)(bcol + tok) * 128 + hd * 16;
;       unsigned eid[16];
; #pragma unroll
;       for (int k = 0; k < 16; ++k) {
;         const unsigned code = __float_as_uint(v[k]) & 255u;
;         const unsigned i1 = LL[tok * 32 + (((code >> 4) + tok) & 31)] & 127u, i2 = LL[tok * 32 + ((16 + (code & 15u) + tok) & 31)] & 127u;
;         eid[k] = i1 * 128u + i2;
;       }
	v_add_f32_e32 v147, v137, v134
	v_sub_f32_e32 v134, v138, v145
	v_mul_f32_e32 v134, 0x3fb8aa3b, v134
	v_sub_f32_e32 v135, v139, v145
	v_sub_f32_e32 v138, v140, v145
	v_and_b32_e32 v141, 0xffffff00, v152
	v_exp_f32_e32 v134, v134
	v_mul_f32_e32 v135, 0x3fb8aa3b, v135
	v_mul_f32_e32 v138, 0x3fb8aa3b, v138
	v_exp_f32_e32 v135, v135
	v_exp_f32_e32 v140, v138
	v_sub_f32_e32 v138, v141, v145
	v_mul_f32_e32 v138, 0x3fb8aa3b, v138
	v_exp_f32_e32 v141, v138
	v_add_f32_e32 v138, v134, v147
	v_add_f32_e32 v138, v135, v138
	v_and_b32_e32 v142, 0xffffff00, v154
	v_add_f32_e32 v138, v140, v138
	v_and_b32_e32 v143, 0xffffff00, v153
	v_add_f32_e32 v147, v141, v138
	v_sub_f32_e32 v138, v142, v145
	v_and_b32_e32 v144, 0xffffff00, v156
	v_mul_f32_e32 v138, 0x3fb8aa3b, v138
	v_sub_f32_e32 v139, v143, v145
	v_and_b32_e32 v146, 0xffffff00, v157
	v_exp_f32_e32 v138, v138
	v_mul_f32_e32 v139, 0x3fb8aa3b, v139
	v_sub_f32_e32 v142, v144, v145
	v_exp_f32_e32 v139, v139
	v_mul_f32_e32 v142, 0x3fb8aa3b, v142
	v_sub_f32_e32 v143, v146, v145
	v_exp_f32_e32 v142, v142
	v_mul_f32_e32 v143, 0x3fb8aa3b, v143
	v_exp_f32_e32 v143, v143
	v_add_f32_e32 v144, v138, v147
	v_add_f32_e32 v144, v139, v144
	v_add_f32_e32 v144, v142, v144
	v_add_f32_e32 v170, v143, v144
	v_or_b32_e32 v144, s78, v164
	v_bfe_u32 v164, v169, 4, 4
	v_or_b32_e32 v169, 16, v169
	v_bfe_u32 v171, v168, 4, 4
	v_or_b32_e32 v168, 16, v168
	v_bfe_u32 v172, v167, 4, 4
	v_or_b32_e32 v167, 16, v167
	v_bfe_u32 v173, v166, 4, 4
	v_or_b32_e32 v166, 16, v166
	v_add_u32_e32 v164, v164, v163
	v_add_u32_e32 v169, v169, v163
	v_add_u32_e32 v171, v171, v163
	v_add_u32_e32 v168, v168, v163
	v_add_u32_e32 v172, v172, v163
	v_add_u32_e32 v167, v167, v163
	v_add_u32_e32 v173, v173, v163
	v_add_u32_e32 v166, v166, v163
	v_and_b32_e32 v164, 31, v164
	v_and_b32_e32 v169, 31, v169
	v_and_b32_e32 v171, 31, v171
	v_and_b32_e32 v168, 31, v168
	v_and_b32_e32 v172, 31, v172
	v_and_b32_e32 v167, 31, v167
	v_and_b32_e32 v173, 31, v173
	v_and_b32_e32 v166, 31, v166
	v_lshl_add_u32 v164, v164, 2, v165
	v_lshl_add_u32 v169, v169, 2, v165
	v_lshl_add_u32 v171, v171, 2, v165
	v_lshl_add_u32 v168, v168, 2, v165
	v_lshl_add_u32 v172, v172, 2, v165
	v_lshl_add_u32 v167, v167, 2, v165
	v_lshl_add_u32 v173, v173, 2, v165
	v_lshl_add_u32 v166, v166, 2, v165
	ds_read_b32 v164, v164
	ds_read_b32 v169, v169
	ds_read_b32 v171, v171
	ds_read_b32 v168, v168
	ds_read_b32 v172, v172
	ds_read_b32 v167, v167
	ds_read_b32 v173, v173
	ds_read_b32 v166, v166
	s_waitcnt lgkmcnt(6)
	v_and_b32_e32 v169, 0x7f, v169
	v_lshlrev_b32_e32 v164, 7, v164
	v_and_or_b32 v164, v164, s40, v169
	s_waitcnt lgkmcnt(4)
	v_and_b32_e32 v168, 0x7f, v168
	v_lshlrev_b32_e32 v169, 7, v171
	v_and_or_b32 v168, v169, s40, v168
	s_waitcnt lgkmcnt(2)
	v_and_b32_e32 v167, 0x7f, v167
	v_lshlrev_b32_e32 v169, 7, v172
	v_and_or_b32 v167, v169, s40, v167
	s_waitcnt lgkmcnt(0)
	v_and_b32_e32 v166, 0x7f, v166
	v_lshlrev_b32_e32 v169, 7, v173
	v_and_or_b32 v166, v169, s40, v166
	v_bfe_u32 v169, v151, 4, 4
	v_or_b32_e32 v151, 16, v151
	v_bfe_u32 v171, v150, 4, 4
	v_or_b32_e32 v150, 16, v150
	v_bfe_u32 v172, v149, 4, 4
	v_or_b32_e32 v149, 16, v149
	v_bfe_u32 v173, v148, 4, 4
	v_or_b32_e32 v148, 16, v148
	v_add_u32_e32 v169, v169, v163
	v_add_u32_e32 v151, v151, v163
	v_add_u32_e32 v171, v171, v163
	v_add_u32_e32 v150, v150, v163
	v_add_u32_e32 v172, v172, v163
	v_add_u32_e32 v149, v149, v163
	v_add_u32_e32 v173, v173, v163
	v_add_u32_e32 v148, v148, v163
	v_and_b32_e32 v169, 31, v169
	v_and_b32_e32 v151, 31, v151
	v_and_b32_e32 v171, 31, v171
	v_and_b32_e32 v150, 31, v150
	v_and_b32_e32 v172, 31, v172
	v_and_b32_e32 v149, 31, v149
	v_and_b32_e32 v173, 31, v173
	v_and_b32_e32 v148, 31, v148
	v_lshl_add_u32 v169, v169, 2, v165
	v_lshl_add_u32 v151, v151, 2, v165
	v_lshl_add_u32 v171, v171, 2, v165
	v_lshl_add_u32 v150, v150, 2, v165
	v_lshl_add_u32 v172, v172, 2, v165
	v_lshl_add_u32 v149, v149, 2, v165
	v_lshl_add_u32 v173, v173, 2, v165
	v_lshl_add_u32 v148, v148, 2, v165
	ds_read_b32 v169, v169
	ds_read_b32 v151, v151
	ds_read_b32 v171, v171
	ds_read_b32 v150, v150
	ds_read_b32 v172, v172
	ds_read_b32 v149, v149
	ds_read_b32 v173, v173
	ds_read_b32 v148, v148
	s_waitcnt lgkmcnt(6)
	v_and_b32_e32 v151, 0x7f, v151
	v_lshlrev_b32_e32 v169, 7, v169
	v_and_or_b32 v169, v169, s40, v151
	s_waitcnt lgkmcnt(4)
	v_and_b32_e32 v150, 0x7f, v150
	v_lshlrev_b32_e32 v151, 7, v171
	v_and_or_b32 v171, v151, s40, v150
	s_waitcnt lgkmcnt(2)
	v_and_b32_e32 v149, 0x7f, v149
	v_lshlrev_b32_e32 v150, 7, v172
	v_and_or_b32 v149, v150, s40, v149
	s_waitcnt lgkmcnt(0)
; DI void gemm256_tile(const Params& p, int mode, int layer, const u16* R, const u16* Cc, int brow, int bcol, lchar* shm, int tid_in, int wid) {
;     ...
;       const float inv = 1.0f / sum;
;       const int hd = brow >> 8;
;       u16* di = W_IDX(p) + (size_t)(bcol + tok) * 128 + hd * 16;
;       float* dg = W_G(p) + (size_t)(bcol + tok) * 128 + hd * 16;
;       unsigned eid[16];
; #pragma unroll
;       for (int k = 0; k < 16; ++k) {
;         const unsigned code = __float_as_uint(v[k]) & 255u;
;         const unsigned i1 = LL[tok * 32 + (((code >> 4) + tok) & 31)] & 127u, i2 = LL[tok * 32 + ((16 + (code & 15u) + tok) & 31)] & 127u;
;         eid[k] = i1 * 128u + i2;
;       }
; #pragma unroll
;       for (int q = 0; q < 4; ++q) *(f32x4*)(dg + 4 * q) = (f32x4){e[4 * q] * inv, e[4 * q + 1] * inv, e[4 * q + 2] * inv, e[4 * q + 3] * inv};
; #pragma unroll
;       for (int q = 0; q < 2; ++q)
;         *(u32x4*)(di + 8 * q) = (u32x4){eid[8 * q] | (eid[8 * q + 1] << 16), eid[8 * q + 2] | (eid[8 * q + 3] << 16), eid[8 * q + 4] | (eid[8 * q + 5] << 16), eid[8 * q + 6] | (eid[8 * q + 7] << 16)};
	v_and_b32_e32 v148, 0x7f, v148
	v_lshlrev_b32_e32 v150, 7, v173
	v_and_or_b32 v172, v150, s40, v148
	v_bfe_u32 v148, v159, 4, 4
	v_or_b32_e32 v150, 16, v159
	v_bfe_u32 v151, v158, 4, 4
	v_or_b32_e32 v158, 16, v158
	v_bfe_u32 v159, v155, 4, 4
	v_or_b32_e32 v155, 16, v155
	v_bfe_u32 v173, v152, 4, 4
	v_or_b32_e32 v152, 16, v152
	v_add_u32_e32 v148, v148, v163
	v_add_u32_e32 v150, v150, v163
	v_add_u32_e32 v151, v151, v163
	v_add_u32_e32 v158, v158, v163
	v_add_u32_e32 v159, v159, v163
	v_add_u32_e32 v155, v155, v163
	v_add_u32_e32 v173, v173, v163
	v_add_u32_e32 v152, v152, v163
	v_and_b32_e32 v148, 31, v148
	v_and_b32_e32 v150, 31, v150
	v_and_b32_e32 v151, 31, v151
	v_and_b32_e32 v158, 31, v158
	v_and_b32_e32 v159, 31, v159
	v_and_b32_e32 v155, 31, v155
	v_and_b32_e32 v173, 31, v173
	v_and_b32_e32 v152, 31, v152
	v_lshl_add_u32 v148, v148, 2, v165
	v_lshl_add_u32 v150, v150, 2, v165
	v_lshl_add_u32 v151, v151, 2, v165
	v_lshl_add_u32 v158, v158, 2, v165
	v_lshl_add_u32 v159, v159, 2, v165
	v_lshl_add_u32 v155, v155, 2, v165
	v_lshl_add_u32 v173, v173, 2, v165
	v_lshl_add_u32 v152, v152, 2, v165
	ds_read_b32 v148, v148
	ds_read_b32 v150, v150
	ds_read_b32 v151, v151
	ds_read_b32 v158, v158
	ds_read_b32 v159, v159
	ds_read_b32 v155, v155
	ds_read_b32 v173, v173
	ds_read_b32 v152, v152
	s_waitcnt lgkmcnt(6)
	v_and_b32_e32 v150, 0x7f, v150
	v_lshlrev_b32_e32 v148, 7, v148
	v_and_or_b32 v174, v148, s40, v150
	s_waitcnt lgkmcnt(4)
	v_and_b32_e32 v148, 0x7f, v158
	v_lshlrev_b32_e32 v150, 7, v151
	v_and_or_b32 v158, v150, s40, v148
	s_waitcnt lgkmcnt(2)
	v_and_b32_e32 v148, 0x7f, v155
	v_lshlrev_b32_e32 v150, 7, v159
	v_and_or_b32 v155, v150, s40, v148
	s_waitcnt lgkmcnt(0)
	v_and_b32_e32 v148, 0x7f, v152
	v_lshlrev_b32_e32 v150, 7, v173
	v_and_or_b32 v159, v150, s40, v148
	v_bfe_u32 v148, v154, 4, 4
	v_or_b32_e32 v150, 16, v154
	v_bfe_u32 v151, v153, 4, 4
	v_or_b32_e32 v152, 16, v153
	v_bfe_u32 v153, v156, 4, 4
	v_or_b32_e32 v154, 16, v156
	v_bfe_u32 v156, v157, 4, 4
	v_or_b32_e32 v157, 16, v157
	v_add_u32_e32 v148, v148, v163
	v_add_u32_e32 v150, v150, v163
	v_add_u32_e32 v151, v151, v163
	v_add_u32_e32 v152, v152, v163
	v_add_u32_e32 v153, v153, v163
	v_add_u32_e32 v154, v154, v163
	v_add_u32_e32 v156, v156, v163
	v_add_u32_e32 v157, v157, v163
	v_and_b32_e32 v148, 31, v148
	v_and_b32_e32 v150, 31, v150
	v_and_b32_e32 v151, 31, v151
	v_and_b32_e32 v152, 31, v152
	v_and_b32_e32 v153, 31, v153
	v_and_b32_e32 v154, 31, v154
	v_and_b32_e32 v156, 31, v156
	v_and_b32_e32 v157, 31, v157
	v_lshl_add_u32 v148, v148, 2, v165
	v_lshl_add_u32 v150, v150, 2, v165
	v_lshl_add_u32 v151, v151, 2, v165
	v_lshl_add_u32 v152, v152, 2, v165
	v_lshl_add_u32 v153, v153, 2, v165
	v_lshl_add_u32 v154, v154, 2, v165
	v_lshl_add_u32 v156, v156, 2, v165
	v_lshl_add_u32 v157, v157, 2, v165
	ds_read_b32 v148, v148
	ds_read_b32 v150, v150
	ds_read_b32 v151, v151
	ds_read_b32 v152, v152
	ds_read_b32 v153, v153
	ds_read_b32 v154, v154
	ds_read_b32 v156, v156
	ds_read_b32 v157, v157
	s_waitcnt lgkmcnt(6)
	v_and_b32_e32 v150, 0x7f, v150
	v_lshlrev_b32_e32 v148, 7, v148
	v_ashrrev_i32_e32 v145, 31, v144
	v_readlane_b32 s4, v255, 30
	v_and_or_b32 v163, v148, s40, v150
	s_waitcnt lgkmcnt(4)
	v_and_b32_e32 v148, 0x7f, v152
	v_lshlrev_b32_e32 v150, 7, v151
	v_lshlrev_b64 v[146:147], 9, v[144:145]
	v_readlane_b32 s5, v255, 31
	v_and_or_b32 v165, v150, s40, v148
	s_waitcnt lgkmcnt(2)
	v_and_b32_e32 v148, 0x7f, v154
	v_lshlrev_b32_e32 v150, 7, v153
	v_lshl_add_u64 v[146:147], s[4:5], 0, v[146:147]
	v_and_or_b32 v154, v150, s40, v148
	v_div_scale_f32 v148, s[4:5], v170, v170, 1.0
	v_rcp_f32_e32 v150, v148
	s_waitcnt lgkmcnt(0)
	v_and_b32_e32 v151, 0x7f, v157
	v_lshlrev_b32_e32 v152, 7, v156
	v_and_or_b32 v156, v152, s40, v151
	v_fma_f32 v151, -v148, v150, 1.0
	v_fmac_f32_e32 v150, v151, v150
	v_div_scale_f32 v151, vcc, 1.0, v170, 1.0
	v_mul_f32_e32 v152, v151, v150
	v_fma_f32 v153, -v148, v152, v151
	v_fmac_f32_e32 v152, v153, v150
	v_fma_f32 v148, -v148, v152, v151
	s_lshl_b32 s0, s13, 4
	v_div_fmas_f32 v148, v148, v150, v152
	s_ashr_i32 s1, s0, 31
	v_div_fixup_f32 v148, v148, v170, 1.0
	v_lshlrev_b64 v[144:145], 8, v[144:145]
	v_lshl_add_u64 v[152:153], s[0:1], 2, v[146:147]
	v_pk_mul_f32 v[146:147], v[132:133], v[148:149] op_sel_hi:[1,0]
	v_pk_mul_f32 v[132:133], v[136:137], v[148:149] op_sel_hi:[1,0]
	v_pk_mul_f32 v[130:131], v[130:131], v[148:149] op_sel_hi:[1,0]
	v_lshl_add_u64 v[150:151], s[66:67], 0, v[144:145]
	v_pk_mul_f32 v[144:145], v[128:129], v[148:149] op_sel_hi:[1,0]
	global_store_dwordx4 v[152:153], v[130:133], off offset:16
	v_pk_mul_f32 v[128:129], v[134:135], v[148:149] op_sel_hi:[1,0]
	global_store_dwordx4 v[152:153], v[144:147], off
	v_pk_mul_f32 v[130:131], v[140:141], v[148:149] op_sel_hi:[1,0]
	global_store_dwordx4 v[152:153], v[128:131], off offset:32
	v_lshl_add_u64 v[132:133], s[0:1], 1, v[150:151]
	s_nop 0
	v_pk_mul_f32 v[130:131], v[142:143], v[148:149] op_sel_hi:[1,0]
	v_pk_mul_f32 v[128:129], v[138:139], v[148:149] op_sel_hi:[1,0]
	global_store_dwordx4 v[152:153], v[128:131], off offset:48
	s_nop 1
	v_lshl_or_b32 v128, v168, 16, v164
	v_lshl_or_b32 v129, v166, 16, v167
	v_lshl_or_b32 v130, v171, 16, v169
	v_lshl_or_b32 v131, v172, 16, v149
	global_store_dwordx4 v[132:133], v[128:131], off
	s_nop 1
	v_lshl_or_b32 v128, v158, 16, v174
	v_lshl_or_b32 v129, v159, 16, v155
	v_lshl_or_b32 v130, v165, 16, v163
	v_lshl_or_b32 v131, v156, 16, v154
	global_store_dwordx4 v[132:133], v[128:131], off offset:16
